# LRU iteration loads (gate tiles and backward conv taps, fast paths): scalar base + 32-bit lane offset instead of 64-bit per-lane address arithmetic
# baseline (speedup 1.0000x reference)
.LBB0_347:
	s_or_b64 exec, exec, s[36:37]
	s_ashr_i32 s36, s92, 4
	s_mul_i32 s76, s36, 0x480000
	s_mul_hi_i32 s68, s36, 0x480000
	s_add_u32 s37, s64, s76
	s_addc_u32 s73, s65, s68
	s_lshl_b32 s77, s74, 1
	s_add_u32 s72, s37, s77
	v_mov_b32_e32 v34, v32
	v_mov_b32_e32 v35, v32
	s_addc_u32 s73, s73, 0
	v_mov_b32_e32 v33, v32
	v_mov_b64_e32 v[38:39], v[34:35]
	v_lshl_add_u64 v[174:175], v[116:117], 1, s[72:73]
	s_mov_b64 s[100:101], s[72:73]
	v_mov_b64_e32 v[36:37], v[32:33]
	s_and_saveexec_b64 s[72:73], s[10:11]
	s_cbranch_execz .LBB0_349
	global_load_dwordx4 v[36:39], v[174:175], off offset:-2048

.LBB0_390:
	s_mov_b32 s77, s69
	s_lshl_b64 s[76:77], s[76:77], 11
	s_lshl_b32 s78, s98, 17
	s_mov_b32 s79, s69
	v_lshlrev_b32_e32 v0, 1, v116
	s_add_u32 s76, s100, s76
	s_addc_u32 s77, s101, s77
	s_add_u32 s82, s100, s78
	s_addc_u32 s83, s101, s79
	global_load_dwordx4 v[84:87], v0, s[76:77] offset:-2048
	global_load_dwordx4 v[88:91], v0, s[82:83]
	global_load_dwordx4 v[92:95], v0, s[82:83] offset:2048
	s_or_b64 s[36:37], s[36:37], exec
.LBB0_391:
	v_mov_b32_e32 v99, 0
	v_mov_b32_e32 v98, 0
	v_mov_b32_e32 v97, 0
	v_mov_b32_e32 v96, 0
	s_and_saveexec_b64 s[76:77], s[36:37]
	s_cbranch_execz .LBB0_393
	v_lshlrev_b32_e32 v0, 1, v116
	s_add_u32 s82, s100, s78
	s_addc_u32 s83, s101, s79
	s_add_u32 s82, s82, 0x1000
	s_addc_u32 s83, s83, 0
	global_load_dwordx4 v[96:99], v0, s[82:83]

.LBB0_394:
	s_cmp_gt_u32 s97, 19
	v_mov_b32_e32 v100, 0
	s_cselect_b64 s[36:37], -1, 0
	s_cmp_lt_u32 s97, 20
	v_mov_b32_e32 v108, 0
	v_mov_b32_e32 v109, 0
	v_mov_b32_e32 v110, 0
	v_mov_b32_e32 v111, 0
	v_mov_b32_e32 v112, 0
	v_mov_b32_e32 v113, 0
	v_mov_b32_e32 v114, 0
	v_mov_b32_e32 v115, 0
	s_cbranch_scc1 .LBB0_396
	s_lshl_b64 s[76:77], s[68:69], 11
	v_lshlrev_b32_e32 v0, 1, v116
	s_add_u32 s82, s74, s76
	s_addc_u32 s83, s75, s77
	s_add_u32 s76, s72, s76
	s_addc_u32 s77, s73, s77
	global_load_dwordx4 v[112:115], v0, s[82:83]
	global_load_dwordx4 v[108:111], v0, s[76:77]
.LBB0_396:
	s_cmp_gt_u32 s97, 3
	s_cselect_b64 s[76:77], -1, 0
	s_and_b64 s[78:79], s[76:77], exec
	s_cselect_b32 s80, 39, 3
	s_add_i32 s80, s80, s93
	s_sub_i32 s78, s80, 20
	s_cmp_lt_u32 s78, -16
	v_mov_b32_e32 v101, 0
	v_mov_b32_e32 v102, 0
	v_mov_b32_e32 v103, 0
	v_mov_b32_e32 v104, 0
	v_mov_b32_e32 v105, 0
	v_mov_b32_e32 v106, 0
	v_mov_b32_e32 v107, 0
	s_cbranch_scc1 .LBB0_398
	s_lshl_b32 s78, s80, 6
	s_addk_i32 s78, 0xff00
	s_mov_b32 s79, s69
	s_lshl_b64 s[78:79], s[78:79], 11
	v_lshlrev_b32_e32 v0, 1, v116
	s_add_u32 s82, s74, s78
	s_addc_u32 s83, s75, s79
	s_add_u32 s78, s72, s78
	s_addc_u32 s79, s73, s79
	global_load_dwordx4 v[104:107], v0, s[82:83]
	global_load_dwordx4 v[100:103], v0, s[78:79]

	.amdhsa_kernel _Z10hybrid_fwd6Params
		.amdhsa_group_segment_fixed_size 0
		.amdhsa_private_segment_fixed_size 0
		.amdhsa_kernarg_size 464
		.amdhsa_user_sgpr_count 2
		.amdhsa_user_sgpr_dispatch_ptr 0
		.amdhsa_user_sgpr_queue_ptr 0
		.amdhsa_user_sgpr_kernarg_segment_ptr 1
		.amdhsa_user_sgpr_dispatch_id 0
		.amdhsa_user_sgpr_kernarg_preload_length 0
		.amdhsa_user_sgpr_kernarg_preload_offset 0
		.amdhsa_user_sgpr_private_segment_size 0
		.amdhsa_uses_dynamic_stack 0
		.amdhsa_enable_private_segment 0
		.amdhsa_system_sgpr_workgroup_id_x 1
		.amdhsa_system_sgpr_workgroup_id_y 0
		.amdhsa_system_sgpr_workgroup_id_z 0
		.amdhsa_system_sgpr_workgroup_info 0
		.amdhsa_system_vgpr_workitem_id 2
		.amdhsa_next_free_vgpr 256
		.amdhsa_next_free_sgpr 102
		.amdhsa_accum_offset 256
		.amdhsa_reserve_vcc 1
		.amdhsa_float_round_mode_32 0
		.amdhsa_float_round_mode_16_64 0
		.amdhsa_float_denorm_mode_32 3
		.amdhsa_float_denorm_mode_16_64 3
		.amdhsa_dx10_clamp 1
		.amdhsa_ieee_mode 1
		.amdhsa_fp16_overflow 0
		.amdhsa_tg_split 0
		.amdhsa_exception_fp_ieee_invalid_op 0
		.amdhsa_exception_fp_denorm_src 0
		.amdhsa_exception_fp_ieee_div_zero 0
		.amdhsa_exception_fp_ieee_overflow 0
		.amdhsa_exception_fp_ieee_underflow 0
		.amdhsa_exception_fp_ieee_inexact 0
		.amdhsa_exception_int_div_zero 0
	.end_amdhsa_kernel

amdhsa.kernels:
  - .agpr_count:     0
    .args:
      - .offset:         0
        .size:           208
        .value_kind:     by_value
      - .offset:         208
        .size:           4
        .value_kind:     hidden_block_count_x
      - .offset:         212
        .size:           4
        .value_kind:     hidden_block_count_y
      - .offset:         216
        .size:           4
        .value_kind:     hidden_block_count_z
      - .offset:         220
        .size:           2
        .value_kind:     hidden_group_size_x
      - .offset:         222
        .size:           2
        .value_kind:     hidden_group_size_y
      - .offset:         224
        .size:           2
        .value_kind:     hidden_group_size_z
      - .offset:         226
        .size:           2
        .value_kind:     hidden_remainder_x
      - .offset:         228
        .size:           2
        .value_kind:     hidden_remainder_y
      - .offset:         230
        .size:           2
        .value_kind:     hidden_remainder_z
      - .offset:         248
        .size:           8
        .value_kind:     hidden_global_offset_x
      - .offset:         256
        .size:           8
        .value_kind:     hidden_global_offset_y
      - .offset:         264
        .size:           8
        .value_kind:     hidden_global_offset_z
      - .offset:         272
        .size:           2
        .value_kind:     hidden_grid_dims
      - .offset:         296
        .size:           8
        .value_kind:     hidden_multigrid_sync_arg
      - .offset:         328
        .size:           4
        .value_kind:     hidden_dynamic_lds_size
    .group_segment_fixed_size: 0
    .kernarg_segment_align: 8
    .kernarg_segment_size: 464
    .language:       OpenCL C
    .language_version:
      - 2
      - 0
    .max_flat_workgroup_size: 512
    .name:           _Z10hybrid_fwd6Params
    .private_segment_fixed_size: 0
    .sgpr_count:     108
    .sgpr_spill_count: 0
    .symbol:         _Z10hybrid_fwd6Params.kd
    .uniform_work_group_size: 1
    .uses_dynamic_stack: false
    .vgpr_count:     256
    .vgpr_spill_count: 0
    .wavefront_size: 64
